# gate-GEMM output stores (P4 side workgroups) write-through so the XCC's L2 holds fewer dirty lines while the recurrence runs
# baseline (speedup 1.0000x reference)
; __device__ __forceinline__ unsigned pk_bf16(float lo, float hi) { typedef __bf16 b2 __attribute__((ext_vector_type(2))); f32x2 v = {lo, hi}; b2 b = __builtin_convertvector(v, b2); return __builtin_bit_cast(unsigned, b); }
; template <bool WT> __device__ __forceinline__ void store16(void* p, u32x4 v) { if (WT) store16_wt(p, v); else *(u32x4*)p = v; }
; template <int ACT  > __device__ __forceinline__ float act1(float v) { if (ACT == 1) return v * sigm(v); if (ACT == 2) return sigm(v); return v; }
; template <int ACT, bool WT = false> __device__ __forceinline__ void epi_store16(const f32x4 (&acc)[2][2][4][2], u16* base, int pitch, int row0, int col0) {
; #pragma unroll
;     for (int ai = 0; ai < 2; ++ai)
; #pragma unroll
;         for (int m = 0; m < 4; ++m) { u16* rowp = base + (size_t)(row0 + ai * 128 + m * 16) * pitch + col0;
; #pragma unroll
;             for (int bj = 0; bj < 2; ++bj) { const f32x4 v0 = acc[ai][bj][m][0], v1 = acc[ai][bj][m][1]; u32x4 w;
;                 w.x = pk_bf16(act1<ACT>(v0[0]), act1<ACT>(v0[1])); w.y = pk_bf16(act1<ACT>(v0[2]), act1<ACT>(v0[3]));
;                 w.z = pk_bf16(act1<ACT>(v1[0]), act1<ACT>(v1[1])); w.w = pk_bf16(act1<ACT>(v1[2]), act1<ACT>(v1[3]));
;                 store16<WT>(rowp + bj * 128, w); } }
; }
.LBB0_463:
	v_mul_f32_e32 v120, 0xbfb8aa3b, v120
	v_exp_f32_e32 v120, v120
	v_mul_f32_e32 v121, 0xbfb8aa3b, v121
	v_exp_f32_e32 v121, v121
	v_lshl_add_u32 v144, s47, 8, v146
	v_lshl_or_b32 v136, s46, 9, v151
	v_mov_b32_e32 v145, v137
	v_mul_f32_e32 v124, 0xbfb8aa3b, v124
	v_lshl_add_u64 v[142:143], s[0:1], 0, v[136:137]
	v_lshlrev_b64 v[152:153], 12, v[144:145]
	v_exp_f32_e32 v136, v124
	v_mul_f32_e32 v124, 0xbfb8aa3b, v125
	v_add_f32_e32 v120, 1.0, v120
	v_exp_f32_e32 v145, v124
	v_lshl_add_u64 v[124:125], v[142:143], 0, v[152:153]
	v_rcp_f32_e32 v152, v120
	v_add_f32_e32 v120, 1.0, v121
	v_mul_f32_e32 v121, 0xbfb8aa3b, v122
	v_mul_f32_e32 v126, 0xbfb8aa3b, v126
	v_mul_f32_e32 v127, 0xbfb8aa3b, v127
	v_exp_f32_e32 v121, v121
	v_mul_f32_e32 v122, 0xbfb8aa3b, v123
	v_exp_f32_e32 v126, v126
	v_exp_f32_e32 v127, v127
	v_exp_f32_e32 v122, v122
	v_rcp_f32_e32 v123, v120
	v_add_f32_e32 v120, 1.0, v121
	v_add_f32_e32 v136, 1.0, v136
	v_add_f32_e32 v145, 1.0, v145
	v_add_f32_e32 v126, 1.0, v126
	v_add_f32_e32 v127, 1.0, v127
	v_rcp_f32_e32 v153, v120
	v_add_f32_e32 v120, 1.0, v122
	v_mul_f32_e32 v112, 0xbfb8aa3b, v112
	v_rcp_f32_e32 v136, v136
	v_rcp_f32_e32 v145, v145
	v_rcp_f32_e32 v126, v126
	v_rcp_f32_e32 v127, v127
	v_rcp_f32_e32 v154, v120
	v_exp_f32_e32 v112, v112
	v_mul_f32_e32 v113, 0xbfb8aa3b, v113
	v_exp_f32_e32 v113, v113
	v_cvt_pk_bf16_f32 v120, v136, v145
	v_cvt_pk_bf16_f32 v121, v126, v127
	v_cvt_pk_bf16_f32 v122, v152, v123
	v_cvt_pk_bf16_f32 v123, v153, v154
	v_add_f32_e32 v112, 1.0, v112
	global_store_dwordx4 v[124:125], v[120:123], off sc1
	v_mul_f32_e32 v116, 0xbfb8aa3b, v116
	v_mul_f32_e32 v117, 0xbfb8aa3b, v117
	v_rcp_f32_e32 v120, v112
	v_add_f32_e32 v112, 1.0, v113
	v_mul_f32_e32 v113, 0xbfb8aa3b, v114
	v_mul_f32_e32 v118, 0xbfb8aa3b, v118
	v_mul_f32_e32 v119, 0xbfb8aa3b, v119
	v_exp_f32_e32 v113, v113
	v_mul_f32_e32 v114, 0xbfb8aa3b, v115
	v_exp_f32_e32 v116, v116
	v_exp_f32_e32 v117, v117
	v_exp_f32_e32 v118, v118
	v_exp_f32_e32 v119, v119
	v_exp_f32_e32 v114, v114
	v_rcp_f32_e32 v115, v112
	v_add_f32_e32 v112, 1.0, v113
	v_add_f32_e32 v116, 1.0, v116
	v_add_f32_e32 v117, 1.0, v117
	v_add_f32_e32 v118, 1.0, v118
	v_add_f32_e32 v119, 1.0, v119
	v_rcp_f32_e32 v121, v112
	v_add_f32_e32 v112, 1.0, v114
	v_rcp_f32_e32 v116, v116
	v_rcp_f32_e32 v117, v117
	v_rcp_f32_e32 v118, v118
	v_rcp_f32_e32 v119, v119
	v_rcp_f32_e32 v122, v112
	v_mul_f32_e32 v104, 0xbfb8aa3b, v104
	v_cvt_pk_bf16_f32 v112, v116, v117
	v_cvt_pk_bf16_f32 v113, v118, v119
	v_cvt_pk_bf16_f32 v114, v120, v115
	v_cvt_pk_bf16_f32 v115, v121, v122
	v_mul_f32_e32 v108, 0xbfb8aa3b, v108
	v_exp_f32_e32 v104, v104
	v_mul_f32_e32 v105, 0xbfb8aa3b, v105
	global_store_dwordx4 v[124:125], v[112:115], off offset:256 sc1
	v_exp_f32_e32 v105, v105
	v_or_b32_e32 v136, 16, v144
	v_exp_f32_e32 v114, v108
	v_lshlrev_b64 v[112:113], 12, v[136:137]
	v_mul_f32_e32 v108, 0xbfb8aa3b, v109
	v_add_f32_e32 v104, 1.0, v104
	v_exp_f32_e32 v115, v108
	v_lshl_add_u64 v[108:109], v[142:143], 0, v[112:113]
	v_add_f32_e32 v112, 1.0, v114
	v_rcp_f32_e32 v114, v104
	v_add_f32_e32 v104, 1.0, v105
	v_mul_f32_e32 v105, 0xbfb8aa3b, v106
	v_mul_f32_e32 v110, 0xbfb8aa3b, v110
	v_mul_f32_e32 v111, 0xbfb8aa3b, v111
	v_exp_f32_e32 v105, v105
	v_mul_f32_e32 v106, 0xbfb8aa3b, v107
	v_exp_f32_e32 v110, v110
	v_exp_f32_e32 v111, v111
	v_exp_f32_e32 v106, v106
	v_rcp_f32_e32 v107, v104
	v_add_f32_e32 v104, 1.0, v105
	v_add_f32_e32 v113, 1.0, v115
	v_add_f32_e32 v110, 1.0, v110
	v_add_f32_e32 v111, 1.0, v111
	v_rcp_f32_e32 v115, v104
	v_add_f32_e32 v104, 1.0, v106
	v_mul_f32_e32 v96, 0xbfb8aa3b, v96
	v_rcp_f32_e32 v112, v112
	v_rcp_f32_e32 v113, v113
	v_rcp_f32_e32 v110, v110
	v_rcp_f32_e32 v111, v111
	v_rcp_f32_e32 v116, v104
	v_exp_f32_e32 v96, v96
	v_mul_f32_e32 v97, 0xbfb8aa3b, v97
	v_exp_f32_e32 v97, v97
	v_cvt_pk_bf16_f32 v104, v112, v113
	v_cvt_pk_bf16_f32 v105, v110, v111
	v_cvt_pk_bf16_f32 v106, v114, v107
	v_cvt_pk_bf16_f32 v107, v115, v116
	v_add_f32_e32 v96, 1.0, v96
	global_store_dwordx4 v[108:109], v[104:107], off sc1
	v_mul_f32_e32 v100, 0xbfb8aa3b, v100
	v_mul_f32_e32 v101, 0xbfb8aa3b, v101
	v_rcp_f32_e32 v104, v96
	v_add_f32_e32 v96, 1.0, v97
	v_mul_f32_e32 v97, 0xbfb8aa3b, v98
	v_mul_f32_e32 v102, 0xbfb8aa3b, v102
	v_mul_f32_e32 v103, 0xbfb8aa3b, v103
	v_exp_f32_e32 v97, v97
	v_mul_f32_e32 v98, 0xbfb8aa3b, v99
	v_exp_f32_e32 v100, v100
	v_exp_f32_e32 v101, v101
	v_exp_f32_e32 v102, v102
	v_exp_f32_e32 v103, v103
	v_exp_f32_e32 v98, v98
	v_rcp_f32_e32 v99, v96
	v_add_f32_e32 v96, 1.0, v97
	v_add_f32_e32 v100, 1.0, v100
	v_add_f32_e32 v101, 1.0, v101
	v_add_f32_e32 v102, 1.0, v102
	v_add_f32_e32 v103, 1.0, v103
	v_rcp_f32_e32 v105, v96
	v_add_f32_e32 v96, 1.0, v98
	v_rcp_f32_e32 v100, v100
	v_rcp_f32_e32 v101, v101
	v_rcp_f32_e32 v102, v102
	v_rcp_f32_e32 v103, v103
	v_rcp_f32_e32 v106, v96
	v_mul_f32_e32 v88, 0xbfb8aa3b, v88
	v_cvt_pk_bf16_f32 v96, v100, v101
	v_cvt_pk_bf16_f32 v97, v102, v103
	v_cvt_pk_bf16_f32 v98, v104, v99
	v_cvt_pk_bf16_f32 v99, v105, v106
	v_mul_f32_e32 v92, 0xbfb8aa3b, v92
	v_exp_f32_e32 v88, v88
	v_mul_f32_e32 v89, 0xbfb8aa3b, v89
	global_store_dwordx4 v[108:109], v[96:99], off offset:256 sc1
	v_exp_f32_e32 v89, v89
	v_or_b32_e32 v136, 32, v144
	v_exp_f32_e32 v98, v92
	v_lshlrev_b64 v[96:97], 12, v[136:137]
	v_mul_f32_e32 v92, 0xbfb8aa3b, v93
	v_add_f32_e32 v88, 1.0, v88
	v_exp_f32_e32 v99, v92
	v_lshl_add_u64 v[92:93], v[142:143], 0, v[96:97]
	v_add_f32_e32 v96, 1.0, v98
	v_rcp_f32_e32 v98, v88
	v_add_f32_e32 v88, 1.0, v89
	v_mul_f32_e32 v89, 0xbfb8aa3b, v90
	v_mul_f32_e32 v94, 0xbfb8aa3b, v94
	v_mul_f32_e32 v95, 0xbfb8aa3b, v95
	v_exp_f32_e32 v89, v89
; __device__ __forceinline__ unsigned pk_bf16(float lo, float hi) { typedef __bf16 b2 __attribute__((ext_vector_type(2))); f32x2 v = {lo, hi}; b2 b = __builtin_convertvector(v, b2); return __builtin_bit_cast(unsigned, b); }
; template <bool WT> __device__ __forceinline__ void store16(void* p, u32x4 v) { if (WT) store16_wt(p, v); else *(u32x4*)p = v; }
; template <int ACT  > __device__ __forceinline__ float act1(float v) { if (ACT == 1) return v * sigm(v); if (ACT == 2) return sigm(v); return v; }
; template <int ACT, bool WT = false> __device__ __forceinline__ void epi_store16(const f32x4 (&acc)[2][2][4][2], u16* base, int pitch, int row0, int col0) {
; #pragma unroll
;     for (int ai = 0; ai < 2; ++ai)
; #pragma unroll
;         for (int m = 0; m < 4; ++m) { u16* rowp = base + (size_t)(row0 + ai * 128 + m * 16) * pitch + col0;
; #pragma unroll
;             for (int bj = 0; bj < 2; ++bj) { const f32x4 v0 = acc[ai][bj][m][0], v1 = acc[ai][bj][m][1]; u32x4 w;
;                 w.x = pk_bf16(act1<ACT>(v0[0]), act1<ACT>(v0[1])); w.y = pk_bf16(act1<ACT>(v0[2]), act1<ACT>(v0[3]));
;                 w.z = pk_bf16(act1<ACT>(v1[0]), act1<ACT>(v1[1])); w.w = pk_bf16(act1<ACT>(v1[2]), act1<ACT>(v1[3]));
;                 store16<WT>(rowp + bj * 128, w); } }
; }
	v_mul_f32_e32 v90, 0xbfb8aa3b, v91
	v_exp_f32_e32 v94, v94
	v_exp_f32_e32 v95, v95
	v_exp_f32_e32 v90, v90
	v_rcp_f32_e32 v91, v88
	v_add_f32_e32 v88, 1.0, v89
	v_add_f32_e32 v97, 1.0, v99
	v_add_f32_e32 v94, 1.0, v94
	v_add_f32_e32 v95, 1.0, v95
	v_rcp_f32_e32 v99, v88
	v_add_f32_e32 v88, 1.0, v90
	v_mul_f32_e32 v80, 0xbfb8aa3b, v80
	v_rcp_f32_e32 v96, v96
	v_rcp_f32_e32 v97, v97
	v_rcp_f32_e32 v94, v94
	v_rcp_f32_e32 v95, v95
	v_rcp_f32_e32 v100, v88
	v_exp_f32_e32 v80, v80
	v_mul_f32_e32 v81, 0xbfb8aa3b, v81
	v_exp_f32_e32 v81, v81
	v_cvt_pk_bf16_f32 v88, v96, v97
	v_cvt_pk_bf16_f32 v89, v94, v95
	v_cvt_pk_bf16_f32 v90, v98, v91
	v_cvt_pk_bf16_f32 v91, v99, v100
	v_add_f32_e32 v80, 1.0, v80
	global_store_dwordx4 v[92:93], v[88:91], off sc1
	v_mul_f32_e32 v84, 0xbfb8aa3b, v84
	v_mul_f32_e32 v85, 0xbfb8aa3b, v85
	v_rcp_f32_e32 v88, v80
	v_add_f32_e32 v80, 1.0, v81
	v_mul_f32_e32 v81, 0xbfb8aa3b, v82
	v_mul_f32_e32 v86, 0xbfb8aa3b, v86
	v_mul_f32_e32 v87, 0xbfb8aa3b, v87
	v_exp_f32_e32 v81, v81
	v_mul_f32_e32 v82, 0xbfb8aa3b, v83
	v_exp_f32_e32 v84, v84
	v_exp_f32_e32 v85, v85
	v_exp_f32_e32 v86, v86
	v_exp_f32_e32 v87, v87
	v_exp_f32_e32 v82, v82
	v_rcp_f32_e32 v83, v80
	v_add_f32_e32 v80, 1.0, v81
	v_add_f32_e32 v84, 1.0, v84
	v_add_f32_e32 v85, 1.0, v85
	v_add_f32_e32 v86, 1.0, v86
	v_add_f32_e32 v87, 1.0, v87
	v_rcp_f32_e32 v89, v80
	v_add_f32_e32 v80, 1.0, v82
	v_rcp_f32_e32 v84, v84
	v_rcp_f32_e32 v85, v85
	v_rcp_f32_e32 v86, v86
	v_rcp_f32_e32 v87, v87
	v_rcp_f32_e32 v90, v80
	v_mul_f32_e32 v72, 0xbfb8aa3b, v72
	v_cvt_pk_bf16_f32 v80, v84, v85
	v_cvt_pk_bf16_f32 v81, v86, v87
	v_cvt_pk_bf16_f32 v82, v88, v83
	v_cvt_pk_bf16_f32 v83, v89, v90
	v_mul_f32_e32 v76, 0xbfb8aa3b, v76
	v_exp_f32_e32 v72, v72
	v_mul_f32_e32 v73, 0xbfb8aa3b, v73
	global_store_dwordx4 v[92:93], v[80:83], off offset:256 sc1
	v_exp_f32_e32 v73, v73
	v_or_b32_e32 v136, 48, v144
	v_exp_f32_e32 v82, v76
	v_lshlrev_b64 v[80:81], 12, v[136:137]
	v_mul_f32_e32 v76, 0xbfb8aa3b, v77
	v_add_f32_e32 v72, 1.0, v72
	v_exp_f32_e32 v83, v76
	v_lshl_add_u64 v[76:77], v[142:143], 0, v[80:81]
	v_add_f32_e32 v80, 1.0, v82
	v_rcp_f32_e32 v82, v72
	v_add_f32_e32 v72, 1.0, v73
	v_mul_f32_e32 v73, 0xbfb8aa3b, v74
	v_mul_f32_e32 v78, 0xbfb8aa3b, v78
	v_mul_f32_e32 v79, 0xbfb8aa3b, v79
	v_exp_f32_e32 v73, v73
	v_mul_f32_e32 v74, 0xbfb8aa3b, v75
	v_exp_f32_e32 v78, v78
	v_exp_f32_e32 v79, v79
	v_exp_f32_e32 v74, v74
	v_rcp_f32_e32 v75, v72
	v_add_f32_e32 v72, 1.0, v73
	v_add_f32_e32 v81, 1.0, v83
	v_add_f32_e32 v78, 1.0, v78
	v_add_f32_e32 v79, 1.0, v79
	v_rcp_f32_e32 v83, v72
	v_add_f32_e32 v72, 1.0, v74
	v_mul_f32_e32 v64, 0xbfb8aa3b, v64
	v_rcp_f32_e32 v80, v80
	v_rcp_f32_e32 v81, v81
	v_rcp_f32_e32 v78, v78
	v_rcp_f32_e32 v79, v79
	v_rcp_f32_e32 v84, v72
	v_exp_f32_e32 v64, v64
	v_mul_f32_e32 v65, 0xbfb8aa3b, v65
	v_exp_f32_e32 v65, v65
	v_cvt_pk_bf16_f32 v72, v80, v81
	v_cvt_pk_bf16_f32 v73, v78, v79
	v_cvt_pk_bf16_f32 v74, v82, v75
	v_cvt_pk_bf16_f32 v75, v83, v84
	v_add_f32_e32 v64, 1.0, v64
	global_store_dwordx4 v[76:77], v[72:75], off sc1
	v_mul_f32_e32 v68, 0xbfb8aa3b, v68
	v_mul_f32_e32 v69, 0xbfb8aa3b, v69
	v_rcp_f32_e32 v72, v64
	v_add_f32_e32 v64, 1.0, v65
	v_mul_f32_e32 v65, 0xbfb8aa3b, v66
	v_mul_f32_e32 v70, 0xbfb8aa3b, v70
	v_mul_f32_e32 v71, 0xbfb8aa3b, v71
	v_exp_f32_e32 v65, v65
	v_mul_f32_e32 v66, 0xbfb8aa3b, v67
	v_exp_f32_e32 v68, v68
	v_exp_f32_e32 v69, v69
	v_exp_f32_e32 v70, v70
	v_exp_f32_e32 v71, v71
	v_exp_f32_e32 v66, v66
	v_rcp_f32_e32 v67, v64
	v_add_f32_e32 v64, 1.0, v65
	v_add_f32_e32 v68, 1.0, v68
	v_add_f32_e32 v69, 1.0, v69
	v_add_f32_e32 v70, 1.0, v70
	v_add_f32_e32 v71, 1.0, v71
	v_rcp_f32_e32 v73, v64
	v_add_f32_e32 v64, 1.0, v66
	v_rcp_f32_e32 v68, v68
	v_rcp_f32_e32 v69, v69
	v_rcp_f32_e32 v70, v70
	v_rcp_f32_e32 v71, v71
	v_rcp_f32_e32 v74, v64
	v_mul_f32_e32 v56, 0xbfb8aa3b, v56
	v_cvt_pk_bf16_f32 v64, v68, v69
	v_cvt_pk_bf16_f32 v65, v70, v71
	v_cvt_pk_bf16_f32 v66, v72, v67
	v_cvt_pk_bf16_f32 v67, v73, v74
	v_mul_f32_e32 v60, 0xbfb8aa3b, v60
	v_exp_f32_e32 v56, v56
	v_mul_f32_e32 v57, 0xbfb8aa3b, v57
	global_store_dwordx4 v[76:77], v[64:67], off offset:256 sc1
	v_exp_f32_e32 v57, v57
	v_add_u32_e32 v136, 0x80, v144
	v_exp_f32_e32 v66, v60
	v_lshlrev_b64 v[64:65], 12, v[136:137]
	v_mul_f32_e32 v60, 0xbfb8aa3b, v61
	v_add_f32_e32 v56, 1.0, v56
	v_exp_f32_e32 v67, v60
	v_lshl_add_u64 v[60:61], v[142:143], 0, v[64:65]
	v_add_f32_e32 v64, 1.0, v66
	v_rcp_f32_e32 v66, v56
	v_add_f32_e32 v56, 1.0, v57
	v_mul_f32_e32 v57, 0xbfb8aa3b, v58
	v_mul_f32_e32 v62, 0xbfb8aa3b, v62
	v_mul_f32_e32 v63, 0xbfb8aa3b, v63
	v_exp_f32_e32 v57, v57
	v_mul_f32_e32 v58, 0xbfb8aa3b, v59
	v_exp_f32_e32 v62, v62
	v_exp_f32_e32 v63, v63
	v_exp_f32_e32 v58, v58
	v_rcp_f32_e32 v59, v56
	v_add_f32_e32 v56, 1.0, v57
	v_add_f32_e32 v65, 1.0, v67
	v_add_f32_e32 v62, 1.0, v62
	v_add_f32_e32 v63, 1.0, v63
	v_rcp_f32_e32 v67, v56
	v_add_f32_e32 v56, 1.0, v58
	v_mul_f32_e32 v48, 0xbfb8aa3b, v48
	v_rcp_f32_e32 v64, v64
	v_rcp_f32_e32 v65, v65
	v_rcp_f32_e32 v62, v62
	v_rcp_f32_e32 v63, v63
	v_rcp_f32_e32 v68, v56
	v_exp_f32_e32 v48, v48
	v_mul_f32_e32 v49, 0xbfb8aa3b, v49
	v_exp_f32_e32 v49, v49
	v_cvt_pk_bf16_f32 v56, v64, v65
	v_cvt_pk_bf16_f32 v57, v62, v63
	v_cvt_pk_bf16_f32 v58, v66, v59
	v_cvt_pk_bf16_f32 v59, v67, v68
	v_add_f32_e32 v48, 1.0, v48
	global_store_dwordx4 v[60:61], v[56:59], off sc1
	v_mul_f32_e32 v52, 0xbfb8aa3b, v52
	v_mul_f32_e32 v53, 0xbfb8aa3b, v53
	v_rcp_f32_e32 v56, v48
	v_add_f32_e32 v48, 1.0, v49
	v_mul_f32_e32 v49, 0xbfb8aa3b, v50
	v_mul_f32_e32 v54, 0xbfb8aa3b, v54
	v_mul_f32_e32 v55, 0xbfb8aa3b, v55
	v_exp_f32_e32 v49, v49
	v_mul_f32_e32 v50, 0xbfb8aa3b, v51
; __device__ __forceinline__ unsigned pk_bf16(float lo, float hi) { typedef __bf16 b2 __attribute__((ext_vector_type(2))); f32x2 v = {lo, hi}; b2 b = __builtin_convertvector(v, b2); return __builtin_bit_cast(unsigned, b); }
; template <bool WT> __device__ __forceinline__ void store16(void* p, u32x4 v) { if (WT) store16_wt(p, v); else *(u32x4*)p = v; }
; template <int ACT  > __device__ __forceinline__ float act1(float v) { if (ACT == 1) return v * sigm(v); if (ACT == 2) return sigm(v); return v; }
; template <int ACT, bool WT = false> __device__ __forceinline__ void epi_store16(const f32x4 (&acc)[2][2][4][2], u16* base, int pitch, int row0, int col0) {
; #pragma unroll
;     for (int ai = 0; ai < 2; ++ai)
; #pragma unroll
;         for (int m = 0; m < 4; ++m) { u16* rowp = base + (size_t)(row0 + ai * 128 + m * 16) * pitch + col0;
; #pragma unroll
;             for (int bj = 0; bj < 2; ++bj) { const f32x4 v0 = acc[ai][bj][m][0], v1 = acc[ai][bj][m][1]; u32x4 w;
;                 w.x = pk_bf16(act1<ACT>(v0[0]), act1<ACT>(v0[1])); w.y = pk_bf16(act1<ACT>(v0[2]), act1<ACT>(v0[3]));
;                 w.z = pk_bf16(act1<ACT>(v1[0]), act1<ACT>(v1[1])); w.w = pk_bf16(act1<ACT>(v1[2]), act1<ACT>(v1[3]));
;                 store16<WT>(rowp + bj * 128, w); } }
; }
	v_exp_f32_e32 v52, v52
	v_exp_f32_e32 v53, v53
	v_exp_f32_e32 v54, v54
	v_exp_f32_e32 v55, v55
	v_exp_f32_e32 v50, v50
	v_rcp_f32_e32 v51, v48
	v_add_f32_e32 v48, 1.0, v49
	v_add_f32_e32 v52, 1.0, v52
	v_add_f32_e32 v53, 1.0, v53
	v_add_f32_e32 v54, 1.0, v54
	v_add_f32_e32 v55, 1.0, v55
	v_rcp_f32_e32 v57, v48
	v_add_f32_e32 v48, 1.0, v50
	v_rcp_f32_e32 v52, v52
	v_rcp_f32_e32 v53, v53
	v_rcp_f32_e32 v54, v54
	v_rcp_f32_e32 v55, v55
	v_rcp_f32_e32 v58, v48
	v_mul_f32_e32 v40, 0xbfb8aa3b, v40
	v_cvt_pk_bf16_f32 v48, v52, v53
	v_cvt_pk_bf16_f32 v49, v54, v55
	v_cvt_pk_bf16_f32 v50, v56, v51
	v_cvt_pk_bf16_f32 v51, v57, v58
	v_mul_f32_e32 v44, 0xbfb8aa3b, v44
	v_exp_f32_e32 v40, v40
	v_mul_f32_e32 v41, 0xbfb8aa3b, v41
	global_store_dwordx4 v[60:61], v[48:51], off offset:256 sc1
	v_exp_f32_e32 v41, v41
	v_add_u32_e32 v136, 0x90, v144
	v_exp_f32_e32 v50, v44
	v_lshlrev_b64 v[48:49], 12, v[136:137]
	v_mul_f32_e32 v44, 0xbfb8aa3b, v45
	v_add_f32_e32 v40, 1.0, v40
	v_exp_f32_e32 v51, v44
	v_lshl_add_u64 v[44:45], v[142:143], 0, v[48:49]
	v_add_f32_e32 v48, 1.0, v50
	v_rcp_f32_e32 v50, v40
	v_add_f32_e32 v40, 1.0, v41
	v_mul_f32_e32 v41, 0xbfb8aa3b, v42
	v_mul_f32_e32 v46, 0xbfb8aa3b, v46
	v_mul_f32_e32 v47, 0xbfb8aa3b, v47
	v_exp_f32_e32 v41, v41
	v_mul_f32_e32 v42, 0xbfb8aa3b, v43
	v_exp_f32_e32 v46, v46
	v_exp_f32_e32 v47, v47
	v_exp_f32_e32 v42, v42
	v_rcp_f32_e32 v43, v40
	v_add_f32_e32 v40, 1.0, v41
	v_add_f32_e32 v49, 1.0, v51
	v_add_f32_e32 v46, 1.0, v46
	v_add_f32_e32 v47, 1.0, v47
	v_rcp_f32_e32 v51, v40
	v_add_f32_e32 v40, 1.0, v42
	v_mul_f32_e32 v32, 0xbfb8aa3b, v32
	v_rcp_f32_e32 v48, v48
	v_rcp_f32_e32 v49, v49
	v_rcp_f32_e32 v46, v46
	v_rcp_f32_e32 v47, v47
	v_rcp_f32_e32 v52, v40
	v_exp_f32_e32 v32, v32
	v_mul_f32_e32 v33, 0xbfb8aa3b, v33
	v_exp_f32_e32 v33, v33
	v_cvt_pk_bf16_f32 v40, v48, v49
	v_cvt_pk_bf16_f32 v41, v46, v47
	v_cvt_pk_bf16_f32 v42, v50, v43
	v_cvt_pk_bf16_f32 v43, v51, v52
	v_add_f32_e32 v32, 1.0, v32
	global_store_dwordx4 v[44:45], v[40:43], off sc1
	v_mul_f32_e32 v36, 0xbfb8aa3b, v36
	v_mul_f32_e32 v37, 0xbfb8aa3b, v37
	v_rcp_f32_e32 v40, v32
	v_add_f32_e32 v32, 1.0, v33
	v_mul_f32_e32 v33, 0xbfb8aa3b, v34
	v_mul_f32_e32 v38, 0xbfb8aa3b, v38
	v_mul_f32_e32 v39, 0xbfb8aa3b, v39
	v_exp_f32_e32 v33, v33
	v_mul_f32_e32 v34, 0xbfb8aa3b, v35
	v_exp_f32_e32 v36, v36
	v_exp_f32_e32 v37, v37
	v_exp_f32_e32 v38, v38
	v_exp_f32_e32 v39, v39
	v_exp_f32_e32 v34, v34
	v_rcp_f32_e32 v35, v32
	v_add_f32_e32 v32, 1.0, v33
	v_add_f32_e32 v36, 1.0, v36
	v_add_f32_e32 v37, 1.0, v37
	v_add_f32_e32 v38, 1.0, v38
	v_add_f32_e32 v39, 1.0, v39
	v_rcp_f32_e32 v41, v32
	v_add_f32_e32 v32, 1.0, v34
	v_rcp_f32_e32 v36, v36
	v_rcp_f32_e32 v37, v37
	v_rcp_f32_e32 v38, v38
	v_rcp_f32_e32 v39, v39
	v_rcp_f32_e32 v42, v32
	v_mul_f32_e32 v24, 0xbfb8aa3b, v24
	v_cvt_pk_bf16_f32 v32, v36, v37
	v_cvt_pk_bf16_f32 v33, v38, v39
	v_cvt_pk_bf16_f32 v34, v40, v35
	v_cvt_pk_bf16_f32 v35, v41, v42
	v_mul_f32_e32 v28, 0xbfb8aa3b, v28
	v_exp_f32_e32 v24, v24
	v_mul_f32_e32 v25, 0xbfb8aa3b, v25
	global_store_dwordx4 v[44:45], v[32:35], off offset:256 sc1
	v_exp_f32_e32 v25, v25
	v_add_u32_e32 v136, 0xa0, v144
	v_exp_f32_e32 v34, v28
	v_lshlrev_b64 v[32:33], 12, v[136:137]
	v_mul_f32_e32 v28, 0xbfb8aa3b, v29
	v_add_f32_e32 v24, 1.0, v24
	v_exp_f32_e32 v35, v28
	v_lshl_add_u64 v[28:29], v[142:143], 0, v[32:33]
	v_add_f32_e32 v32, 1.0, v34
	v_rcp_f32_e32 v34, v24
	v_add_f32_e32 v24, 1.0, v25
	v_mul_f32_e32 v25, 0xbfb8aa3b, v26
	v_mul_f32_e32 v30, 0xbfb8aa3b, v30
	v_mul_f32_e32 v31, 0xbfb8aa3b, v31
	v_exp_f32_e32 v25, v25
	v_mul_f32_e32 v26, 0xbfb8aa3b, v27
	v_exp_f32_e32 v30, v30
	v_exp_f32_e32 v31, v31
	v_exp_f32_e32 v26, v26
	v_rcp_f32_e32 v27, v24
	v_add_f32_e32 v24, 1.0, v25
	v_add_f32_e32 v33, 1.0, v35
	v_add_f32_e32 v30, 1.0, v30
	v_add_f32_e32 v31, 1.0, v31
; __device__ __forceinline__ unsigned pk_bf16(float lo, float hi) { typedef __bf16 b2 __attribute__((ext_vector_type(2))); f32x2 v = {lo, hi}; b2 b = __builtin_convertvector(v, b2); return __builtin_bit_cast(unsigned, b); }
; template <bool WT> __device__ __forceinline__ void store16(void* p, u32x4 v) { if (WT) store16_wt(p, v); else *(u32x4*)p = v; }
; template <int ACT  > __device__ __forceinline__ float act1(float v) { if (ACT == 1) return v * sigm(v); if (ACT == 2) return sigm(v); return v; }
; template <int ACT, bool WT = false> __device__ __forceinline__ void epi_store16(const f32x4 (&acc)[2][2][4][2], u16* base, int pitch, int row0, int col0) {
; #pragma unroll
;     for (int ai = 0; ai < 2; ++ai)
; #pragma unroll
;         for (int m = 0; m < 4; ++m) { u16* rowp = base + (size_t)(row0 + ai * 128 + m * 16) * pitch + col0;
; #pragma unroll
;             for (int bj = 0; bj < 2; ++bj) { const f32x4 v0 = acc[ai][bj][m][0], v1 = acc[ai][bj][m][1]; u32x4 w;
;                 w.x = pk_bf16(act1<ACT>(v0[0]), act1<ACT>(v0[1])); w.y = pk_bf16(act1<ACT>(v0[2]), act1<ACT>(v0[3]));
;                 w.z = pk_bf16(act1<ACT>(v1[0]), act1<ACT>(v1[1])); w.w = pk_bf16(act1<ACT>(v1[2]), act1<ACT>(v1[3]));
;                 store16<WT>(rowp + bj * 128, w); } }
; }
	v_rcp_f32_e32 v35, v24
	v_add_f32_e32 v24, 1.0, v26
	v_mul_f32_e32 v16, 0xbfb8aa3b, v16
	v_rcp_f32_e32 v32, v32
	v_rcp_f32_e32 v33, v33
	v_rcp_f32_e32 v30, v30
	v_rcp_f32_e32 v31, v31
	v_rcp_f32_e32 v36, v24
	v_exp_f32_e32 v16, v16
	v_mul_f32_e32 v17, 0xbfb8aa3b, v17
	v_exp_f32_e32 v17, v17
	v_cvt_pk_bf16_f32 v24, v32, v33
	v_cvt_pk_bf16_f32 v25, v30, v31
	v_cvt_pk_bf16_f32 v26, v34, v27
	v_cvt_pk_bf16_f32 v27, v35, v36
	v_add_f32_e32 v16, 1.0, v16
	global_store_dwordx4 v[28:29], v[24:27], off sc1
	v_mul_f32_e32 v20, 0xbfb8aa3b, v20
	v_mul_f32_e32 v21, 0xbfb8aa3b, v21
	v_rcp_f32_e32 v24, v16
	v_add_f32_e32 v16, 1.0, v17
	v_mul_f32_e32 v17, 0xbfb8aa3b, v18
	v_mul_f32_e32 v22, 0xbfb8aa3b, v22
	v_mul_f32_e32 v23, 0xbfb8aa3b, v23
	v_exp_f32_e32 v17, v17
	v_mul_f32_e32 v18, 0xbfb8aa3b, v19
	v_exp_f32_e32 v20, v20
	v_exp_f32_e32 v21, v21
	v_exp_f32_e32 v22, v22
	v_exp_f32_e32 v23, v23
	v_exp_f32_e32 v18, v18
	v_rcp_f32_e32 v19, v16
	v_add_f32_e32 v16, 1.0, v17
	v_add_f32_e32 v20, 1.0, v20
	v_add_f32_e32 v21, 1.0, v21
	v_add_f32_e32 v22, 1.0, v22
	v_add_f32_e32 v23, 1.0, v23
	v_rcp_f32_e32 v25, v16
	v_add_f32_e32 v16, 1.0, v18
	v_rcp_f32_e32 v20, v20
	v_rcp_f32_e32 v21, v21
	v_rcp_f32_e32 v22, v22
	v_rcp_f32_e32 v23, v23
	v_rcp_f32_e32 v26, v16
	v_mul_f32_e32 v8, 0xbfb8aa3b, v8
	v_cvt_pk_bf16_f32 v16, v20, v21
	v_cvt_pk_bf16_f32 v17, v22, v23
	v_cvt_pk_bf16_f32 v18, v24, v19
	v_cvt_pk_bf16_f32 v19, v25, v26
	v_mul_f32_e32 v12, 0xbfb8aa3b, v12
	v_exp_f32_e32 v8, v8
	v_mul_f32_e32 v9, 0xbfb8aa3b, v9
	global_store_dwordx4 v[28:29], v[16:19], off offset:256 sc1
	v_exp_f32_e32 v9, v9
	v_add_u32_e32 v136, 0xb0, v144
	v_exp_f32_e32 v18, v12
	v_lshlrev_b64 v[16:17], 12, v[136:137]
	v_mul_f32_e32 v12, 0xbfb8aa3b, v13
	v_add_f32_e32 v8, 1.0, v8
	v_exp_f32_e32 v19, v12
	v_lshl_add_u64 v[12:13], v[142:143], 0, v[16:17]
	v_add_f32_e32 v16, 1.0, v18
	v_rcp_f32_e32 v18, v8
	v_add_f32_e32 v8, 1.0, v9
	v_mul_f32_e32 v9, 0xbfb8aa3b, v10
	v_mul_f32_e32 v14, 0xbfb8aa3b, v14
	v_mul_f32_e32 v15, 0xbfb8aa3b, v15
	v_exp_f32_e32 v9, v9
	v_mul_f32_e32 v10, 0xbfb8aa3b, v11
	v_exp_f32_e32 v14, v14
	v_exp_f32_e32 v15, v15
	v_exp_f32_e32 v10, v10
	v_rcp_f32_e32 v11, v8
	v_add_f32_e32 v8, 1.0, v9
	v_add_f32_e32 v17, 1.0, v19
	v_add_f32_e32 v14, 1.0, v14
	v_add_f32_e32 v15, 1.0, v15
	v_rcp_f32_e32 v19, v8
	v_add_f32_e32 v8, 1.0, v10
	v_mul_f32_e32 v0, 0xbfb8aa3b, v0
	v_rcp_f32_e32 v16, v16
	v_rcp_f32_e32 v17, v17
	v_rcp_f32_e32 v14, v14
	v_rcp_f32_e32 v15, v15
	v_rcp_f32_e32 v20, v8
	v_exp_f32_e32 v0, v0
	v_mul_f32_e32 v1, 0xbfb8aa3b, v1
	v_exp_f32_e32 v1, v1
	v_cvt_pk_bf16_f32 v8, v16, v17
	v_cvt_pk_bf16_f32 v9, v14, v15
	v_cvt_pk_bf16_f32 v10, v18, v11
	v_cvt_pk_bf16_f32 v11, v19, v20
	v_add_f32_e32 v0, 1.0, v0
	global_store_dwordx4 v[12:13], v[8:11], off sc1
	v_mul_f32_e32 v4, 0xbfb8aa3b, v4
	v_mul_f32_e32 v5, 0xbfb8aa3b, v5
	v_rcp_f32_e32 v8, v0
	v_add_f32_e32 v0, 1.0, v1
	v_mul_f32_e32 v1, 0xbfb8aa3b, v2
	v_mul_f32_e32 v6, 0xbfb8aa3b, v6
	v_mul_f32_e32 v7, 0xbfb8aa3b, v7
	v_exp_f32_e32 v1, v1
	v_mul_f32_e32 v2, 0xbfb8aa3b, v3
	v_exp_f32_e32 v4, v4
	v_exp_f32_e32 v5, v5
	v_exp_f32_e32 v6, v6
	v_exp_f32_e32 v7, v7
	v_exp_f32_e32 v2, v2
	v_rcp_f32_e32 v3, v0
	v_add_f32_e32 v0, 1.0, v1
	v_add_f32_e32 v4, 1.0, v4
	v_add_f32_e32 v5, 1.0, v5
	v_add_f32_e32 v6, 1.0, v6
	v_add_f32_e32 v7, 1.0, v7
	v_rcp_f32_e32 v9, v0
	v_add_f32_e32 v0, 1.0, v2
	v_rcp_f32_e32 v4, v4
	v_rcp_f32_e32 v5, v5
	v_rcp_f32_e32 v6, v6
	v_rcp_f32_e32 v7, v7
	v_rcp_f32_e32 v10, v0
	v_cvt_pk_bf16_f32 v0, v4, v5
	v_cvt_pk_bf16_f32 v2, v8, v3
	v_cvt_pk_bf16_f32 v1, v6, v7
	v_cvt_pk_bf16_f32 v3, v9, v10
	s_andn2_b64 vcc, exec, s[18:19]
	s_mov_b64 s[18:19], -1
	global_store_dwordx4 v[12:13], v[0:3], off offset:256 sc1
	s_cbranch_vccnz .LBB0_458
	s_andn2_b64 vcc, exec, s[12:13]
	s_cbranch_vccnz .LBB0_457
	s_barrier
	s_branch .LBB0_457
